# P3 GLA state unit and P13 skip-connection loads re-pipelined; final LayerNorm loop hand-written (hoisted gain/bias, row prefetch, DPP reductions); hipcc regions kept at baseline alignment
# speedup vs baseline: 1.0500x; 1.0089x over previous
.LBB0_780:
	s_movk_i32 s6, 0x7ff
	v_cmp_lt_i32_e32 vcc, s6, v66
	s_and_saveexec_b64 s[6:7], vcc
	s_xor_b64 s[6:7], exec, s[6:7]
	s_cbranch_execz .LBB0_782
	s_movk_i32 s11, 0x80
	v_add_u32_e32 v2, 0xfffff800, v66
	v_bfe_u32 v86, v66, 1, 2
	v_and_or_b32 v67, v77, s11, v1
	v_lshrrev_b32_e32 v87, 3, v2
	v_lshlrev_b32_e32 v2, 6, v67
	v_lshlrev_b32_e32 v3, 14, v86
	v_or3_b32 v89, v3, v2, v68
	v_lshlrev_b32_e32 v90, 4, v87
	v_lshl_or_b32 v88, v86, 13, v68
	v_add_u32_e32 v70, v89, v90
	v_lshlrev_b64 v[2:3], 9, v[70:71]
	v_add_u32_e32 v70, v88, v90
	v_lshlrev_b64 v[6:7], 9, v[70:71]
	v_lshl_add_u64 v[2:3], v[72:73], 0, v[2:3]
	v_lshl_add_u64 v[6:7], v[74:75], 0, v[6:7]
	s_mov_b64 vcc, 0x1000
	v_lshl_add_u64 v[100:101], v[2:3], 0, vcc
	s_mov_b64 vcc, 0x1000
	v_lshl_add_u64 v[102:103], v[6:7], 0, vcc
	s_mov_b64 vcc, 0x101000
	v_lshl_add_u64 v[104:105], v[6:7], 0, vcc
	s_mov_b64 vcc, 0x201000
	v_lshl_add_u64 v[106:107], v[6:7], 0, vcc
	s_mov_b64 vcc, 0x301000
	v_lshl_add_u64 v[108:109], v[6:7], 0, vcc
	global_load_dwordx4 v[112:115], v[100:101], off offset:-4096
	global_load_dwordx4 v[116:119], v[100:101], off offset:-3072
	global_load_dwordx4 v[144:147], v[102:103], off offset:-4096
	global_load_dwordx4 v[148:151], v[104:105], off offset:-4096
	global_load_dwordx4 v[152:155], v[106:107], off offset:-4096
	global_load_dwordx4 v[156:159], v[108:109], off offset:-4096
	global_load_dwordx4 v[120:123], v[100:101], off offset:-2048
	global_load_dwordx4 v[124:127], v[100:101], off offset:-1024
	global_load_dwordx4 v[128:131], v[100:101], off
	global_load_dwordx4 v[132:135], v[100:101], off offset:1024
	global_load_dwordx4 v[136:139], v[100:101], off offset:2048
	global_load_dwordx4 v[140:143], v[100:101], off offset:3072
	global_load_dwordx4 v[160:163], v[102:103], off offset:-3072
	global_load_dwordx4 v[164:167], v[104:105], off offset:-3072
	global_load_dwordx4 v[168:171], v[106:107], off offset:-3072
	global_load_dwordx4 v[172:175], v[108:109], off offset:-3072
	global_load_dwordx4 v[176:179], v[102:103], off offset:-2048
	global_load_dwordx4 v[180:183], v[104:105], off offset:-2048
	global_load_dwordx4 v[184:187], v[106:107], off offset:-2048
	global_load_dwordx4 v[188:191], v[108:109], off offset:-2048
	s_waitcnt vmcnt(17)
	v_mfma_f32_32x32x16_bf16 v[50:65], v[144:147], v[112:115], 0
	global_load_dwordx4 v[144:147], v[102:103], off offset:-1024
	s_waitcnt vmcnt(17)
	v_mfma_f32_32x32x16_bf16 v[34:49], v[148:151], v[112:115], 0
	global_load_dwordx4 v[148:151], v[104:105], off offset:-1024
	s_waitcnt vmcnt(17)
	v_mfma_f32_32x32x16_bf16 v[18:33], v[152:155], v[112:115], 0
	global_load_dwordx4 v[152:155], v[106:107], off offset:-1024
	s_waitcnt vmcnt(17)
	v_mfma_f32_32x32x16_bf16 v[2:17], v[156:159], v[112:115], 0
	global_load_dwordx4 v[156:159], v[108:109], off offset:-1024
	s_waitcnt vmcnt(11)
	v_mfma_f32_32x32x16_bf16 v[50:65], v[160:163], v[116:119], v[50:65]
	global_load_dwordx4 v[160:163], v[102:103], off
	s_waitcnt vmcnt(11)
	v_mfma_f32_32x32x16_bf16 v[34:49], v[164:167], v[116:119], v[34:49]
	global_load_dwordx4 v[164:167], v[104:105], off
	s_waitcnt vmcnt(11)
	v_mfma_f32_32x32x16_bf16 v[18:33], v[168:171], v[116:119], v[18:33]
	global_load_dwordx4 v[168:171], v[106:107], off
	s_waitcnt vmcnt(11)
	v_mfma_f32_32x32x16_bf16 v[2:17], v[172:175], v[116:119], v[2:17]
	global_load_dwordx4 v[172:175], v[108:109], off
	s_waitcnt vmcnt(11)
	v_mfma_f32_32x32x16_bf16 v[50:65], v[176:179], v[120:123], v[50:65]
	global_load_dwordx4 v[176:179], v[102:103], off offset:1024
	s_waitcnt vmcnt(11)
	v_mfma_f32_32x32x16_bf16 v[34:49], v[180:183], v[120:123], v[34:49]
	global_load_dwordx4 v[180:183], v[104:105], off offset:1024
	s_waitcnt vmcnt(11)
	v_mfma_f32_32x32x16_bf16 v[18:33], v[184:187], v[120:123], v[18:33]
	global_load_dwordx4 v[184:187], v[106:107], off offset:1024
	s_waitcnt vmcnt(11)
	v_mfma_f32_32x32x16_bf16 v[2:17], v[188:191], v[120:123], v[2:17]
	global_load_dwordx4 v[188:191], v[108:109], off offset:1024
	s_waitcnt vmcnt(11)
	v_mfma_f32_32x32x16_bf16 v[50:65], v[144:147], v[124:127], v[50:65]
	global_load_dwordx4 v[144:147], v[102:103], off offset:2048
	s_waitcnt vmcnt(11)
	v_mfma_f32_32x32x16_bf16 v[34:49], v[148:151], v[124:127], v[34:49]
	global_load_dwordx4 v[148:151], v[104:105], off offset:2048
	s_waitcnt vmcnt(11)
	v_mfma_f32_32x32x16_bf16 v[18:33], v[152:155], v[124:127], v[18:33]
	global_load_dwordx4 v[152:155], v[106:107], off offset:2048
	s_waitcnt vmcnt(11)
	v_mfma_f32_32x32x16_bf16 v[2:17], v[156:159], v[124:127], v[2:17]
	global_load_dwordx4 v[156:159], v[108:109], off offset:2048
	s_waitcnt vmcnt(11)
	v_mfma_f32_32x32x16_bf16 v[50:65], v[160:163], v[128:131], v[50:65]
	global_load_dwordx4 v[160:163], v[102:103], off offset:3072
	s_waitcnt vmcnt(11)
	v_mfma_f32_32x32x16_bf16 v[34:49], v[164:167], v[128:131], v[34:49]
	global_load_dwordx4 v[164:167], v[104:105], off offset:3072
	s_waitcnt vmcnt(11)
	v_mfma_f32_32x32x16_bf16 v[18:33], v[168:171], v[128:131], v[18:33]
	global_load_dwordx4 v[168:171], v[106:107], off offset:3072
	s_waitcnt vmcnt(11)
	v_mfma_f32_32x32x16_bf16 v[2:17], v[172:175], v[128:131], v[2:17]
	global_load_dwordx4 v[172:175], v[108:109], off offset:3072
	s_waitcnt vmcnt(11)
	v_mfma_f32_32x32x16_bf16 v[50:65], v[176:179], v[132:135], v[50:65]
	s_waitcnt vmcnt(10)
	v_mfma_f32_32x32x16_bf16 v[34:49], v[180:183], v[132:135], v[34:49]
	s_waitcnt vmcnt(9)
	v_mfma_f32_32x32x16_bf16 v[18:33], v[184:187], v[132:135], v[18:33]
	s_waitcnt vmcnt(8)
	v_mfma_f32_32x32x16_bf16 v[2:17], v[188:191], v[132:135], v[2:17]
	s_waitcnt vmcnt(7)
	v_mfma_f32_32x32x16_bf16 v[50:65], v[144:147], v[136:139], v[50:65]
	s_waitcnt vmcnt(6)
	v_mfma_f32_32x32x16_bf16 v[34:49], v[148:151], v[136:139], v[34:49]
	s_waitcnt vmcnt(5)
	v_mfma_f32_32x32x16_bf16 v[18:33], v[152:155], v[136:139], v[18:33]
	s_waitcnt vmcnt(4)
	v_mfma_f32_32x32x16_bf16 v[2:17], v[156:159], v[136:139], v[2:17]
	s_waitcnt vmcnt(3)
	v_mfma_f32_32x32x16_bf16 v[50:65], v[160:163], v[140:143], v[50:65]
	s_waitcnt vmcnt(2)
	v_mfma_f32_32x32x16_bf16 v[34:49], v[164:167], v[140:143], v[34:49]
	s_waitcnt vmcnt(1)
	v_mfma_f32_32x32x16_bf16 v[18:33], v[168:171], v[140:143], v[18:33]
	s_waitcnt vmcnt(0)
	v_mfma_f32_32x32x16_bf16 v[2:17], v[172:175], v[140:143], v[2:17]
	s_movk_i32 s11, 0x1000
	v_lshl_or_b32 v70, v87, 2, v86
	v_lshlrev_b64 v[86:87], 16, v[70:71]
	v_lshl_add_u64 v[86:87], s[68:69], 0, v[86:87]
	v_lshl_or_b32 v70, v67, 8, v85
	v_lshl_add_u64 v[192:193], v[86:87], 0, v[70:71]
	s_mov_b64 vcc, 0x1000
	v_lshl_add_u64 v[194:195], v[192:193], 0, vcc
	s_nop 7
	s_nop 7
	v_cvt_pk_bf16_f32 v196, v50, v51
	v_cvt_pk_bf16_f32 v197, v52, v53
	global_store_dwordx2 v[192:193], v[196:197], off
	v_cvt_pk_bf16_f32 v198, v54, v55
	v_cvt_pk_bf16_f32 v199, v56, v57
	global_store_dwordx2 v[192:193], v[198:199], off offset:512
	v_cvt_pk_bf16_f32 v200, v58, v59
	v_cvt_pk_bf16_f32 v201, v60, v61
	global_store_dwordx2 v[192:193], v[200:201], off offset:1024
	v_cvt_pk_bf16_f32 v202, v62, v63
	v_cvt_pk_bf16_f32 v203, v64, v65
	global_store_dwordx2 v[192:193], v[202:203], off offset:1536
	v_cvt_pk_bf16_f32 v196, v34, v35
	v_cvt_pk_bf16_f32 v197, v36, v37
	global_store_dwordx2 v[192:193], v[196:197], off offset:2048
	v_cvt_pk_bf16_f32 v198, v38, v39
	v_cvt_pk_bf16_f32 v199, v40, v41
	global_store_dwordx2 v[192:193], v[198:199], off offset:2560
	v_cvt_pk_bf16_f32 v200, v42, v43
	v_cvt_pk_bf16_f32 v201, v44, v45
	global_store_dwordx2 v[192:193], v[200:201], off offset:3072
	v_cvt_pk_bf16_f32 v202, v46, v47
	v_cvt_pk_bf16_f32 v203, v48, v49
	global_store_dwordx2 v[192:193], v[202:203], off offset:3584
	v_cvt_pk_bf16_f32 v196, v18, v19
	v_cvt_pk_bf16_f32 v197, v20, v21
	global_store_dwordx2 v[194:195], v[196:197], off
	v_cvt_pk_bf16_f32 v198, v22, v23
	v_cvt_pk_bf16_f32 v199, v24, v25
	global_store_dwordx2 v[194:195], v[198:199], off offset:512
	v_cvt_pk_bf16_f32 v200, v26, v27
	v_cvt_pk_bf16_f32 v201, v28, v29
	global_store_dwordx2 v[194:195], v[200:201], off offset:1024
	v_cvt_pk_bf16_f32 v202, v30, v31
	v_cvt_pk_bf16_f32 v203, v32, v33
	global_store_dwordx2 v[194:195], v[202:203], off offset:1536
	v_cvt_pk_bf16_f32 v196, v2, v3
	v_cvt_pk_bf16_f32 v197, v4, v5
	global_store_dwordx2 v[194:195], v[196:197], off offset:2048
	v_cvt_pk_bf16_f32 v198, v6, v7
	v_cvt_pk_bf16_f32 v199, v8, v9
	global_store_dwordx2 v[194:195], v[198:199], off offset:2560
	v_cvt_pk_bf16_f32 v200, v10, v11
	v_cvt_pk_bf16_f32 v201, v12, v13
	global_store_dwordx2 v[194:195], v[200:201], off offset:3072
	v_cvt_pk_bf16_f32 v202, v14, v15
	v_cvt_pk_bf16_f32 v203, v16, v17
	global_store_dwordx2 v[194:195], v[202:203], off offset:3584
	s_nop 0
	s_nop 0
	s_nop 0
	s_nop 0
	s_nop 0
	s_nop 0
	s_nop 0
	s_nop 0
	s_nop 0
	s_nop 0
	s_nop 0

.LBB0_1714:
	v_add_u32_e32 v140, s13, v100
	v_lshlrev_b32_e32 v142, 2, v112
	v_lshl_or_b32 v141, v140, 12, v142
	v_add_u32_e32 v143, 0x1000, v141
	v_add_u32_e32 v144, 0x3000, v141
	v_add_u32_e32 v145, 0x81000, v141
	v_add_u32_e32 v146, 0x83000, v141
	global_load_dword v156, v143, s[66:67] offset:-4096
	global_load_dword v157, v143, s[66:67]
	global_load_dword v158, v144, s[66:67] offset:-4096
	global_load_dword v159, v144, s[66:67]
	global_load_dword v160, v145, s[66:67] offset:-4096
	global_load_dword v161, v145, s[66:67]
	global_load_dword v162, v146, s[66:67] offset:-4096
	global_load_dword v163, v146, s[66:67]
	s_nop 0
	s_nop 0
	s_nop 0
	s_nop 0
	v_pk_mul_f32 v[2:3], v[116:117], v[48:49] op_sel:[0,1]
	v_mfma_f32_32x32x16_bf16 v[32:47], v[18:21], v[64:67], 0
	v_fma_f32 v4, v108, v48, -v2
	v_fma_f32 v5, v109, v49, -v3
	v_fma_f32 v2, v108, v48, v2
	v_fma_f32 v3, v109, v48, v3
	s_waitcnt lgkmcnt(0)
	v_mov_b32_e32 v5, v3
	s_nop 6
	v_mov_b32_e32 v2, v32
	v_mfma_f32_32x32x16_bf16 v[48:63], v[18:21], v[68:71], 0
	v_mov_b32_e32 v24, v34
	s_nop 10
	v_mov_b32_e32 v3, v48
	v_pk_add_f32 v[2:3], v[4:5], v[2:3]
	v_mov_b32_e32 v48, v33
	v_pk_mul_f32 v[4:5], v[116:117], v[2:3] op_sel:[0,1]
	v_cvt_pk_bf16_f32 v133, v2, v3
	v_pk_fma_f32 v[6:7], v[108:109], v[2:3], v[4:5] neg_lo:[0,0,1] neg_hi:[0,0,1]
	v_pk_fma_f32 v[2:3], v[108:109], v[2:3], v[4:5] op_sel_hi:[1,0,1]
	v_mov_b32_e32 v25, v50
	v_mov_b32_e32 v7, v3
	v_pk_add_f32 v[2:3], v[48:49], v[6:7]
	v_mov_b32_e32 v50, v35
	v_pk_mul_f32 v[4:5], v[116:117], v[2:3] op_sel:[0,1]
	v_cvt_pk_bf16_f32 v136, v2, v3
	v_pk_fma_f32 v[22:23], v[108:109], v[2:3], v[4:5] neg_lo:[0,0,1] neg_hi:[0,0,1]
	v_pk_fma_f32 v[2:3], v[108:109], v[2:3], v[4:5] op_sel_hi:[1,0,1]
	s_nop 0
	v_mov_b32_e32 v23, v3
	v_pk_add_f32 v[22:23], v[24:25], v[22:23]
	v_mfma_f32_32x32x16_bf16 v[2:17], v[18:21], v[72:75], 0
	v_mul_f32_e64 v24, v116, v23
	v_mul_f32_e64 v25, v117, v23
	v_cvt_pk_bf16_f32 v137, v22, v23
	v_fma_f32 v48, v108, v22, -v24
	v_fma_f32 v49, v109, v23, -v25
	v_pk_fma_f32 v[134:135], v[108:109], v[22:23], v[24:25] op_sel_hi:[1,0,1]
	s_nop 0
	v_mov_b32_e32 v49, v135
	v_pk_add_f32 v[34:35], v[50:51], v[48:49]
	v_mfma_f32_32x32x16_bf16 v[18:33], v[18:21], v[76:79], 0
	v_mul_f32_e64 v48, v116, v35
	v_mul_f32_e64 v49, v117, v35
	v_cvt_pk_bf16_f32 v134, v34, v35
	v_fma_f32 v50, v108, v34, -v48
	v_fma_f32 v51, v109, v35, -v49
	v_pk_fma_f32 v[34:35], v[108:109], v[34:35], v[48:49] op_sel_hi:[1,0,1]
	s_nop 0
	v_mov_b32_e32 v51, v35
	v_mov_b32_e32 v34, v36
	v_mov_b32_e32 v35, v52
	v_pk_add_f32 v[34:35], v[34:35], v[50:51]
	v_mov_b32_e32 v52, v37
	v_pk_mul_f32 v[48:49], v[116:117], v[34:35] op_sel:[0,1]
	v_cvt_pk_bf16_f32 v135, v34, v35
	v_pk_fma_f32 v[50:51], v[108:109], v[34:35], v[48:49] neg_lo:[0,0,1] neg_hi:[0,0,1]
	v_pk_fma_f32 v[34:35], v[108:109], v[34:35], v[48:49] op_sel_hi:[1,0,1]
	s_nop 0
	v_mov_b32_e32 v51, v35
	v_pk_add_f32 v[34:35], v[52:53], v[50:51]
	s_nop 0
	v_pk_mul_f32 v[36:37], v[116:117], v[34:35] op_sel:[0,1]
	v_cvt_pk_bf16_f32 v50, v34, v35
	v_pk_fma_f32 v[48:49], v[108:109], v[34:35], v[36:37] neg_lo:[0,0,1] neg_hi:[0,0,1]
	v_pk_fma_f32 v[34:35], v[108:109], v[34:35], v[36:37] op_sel_hi:[1,0,1]
	s_nop 0
	v_mov_b32_e32 v49, v35
	v_mov_b32_e32 v34, v38
	v_mov_b32_e32 v35, v54
	v_pk_add_f32 v[34:35], v[34:35], v[48:49]
	v_mov_b32_e32 v54, v39
	v_pk_mul_f32 v[36:37], v[116:117], v[34:35] op_sel:[0,1]
	v_cvt_pk_bf16_f32 v51, v34, v35
	v_pk_fma_f32 v[48:49], v[108:109], v[34:35], v[36:37] neg_lo:[0,0,1] neg_hi:[0,0,1]
	v_pk_fma_f32 v[34:35], v[108:109], v[34:35], v[36:37] op_sel_hi:[1,0,1]
	s_nop 0
	v_mov_b32_e32 v49, v35
	v_pk_add_f32 v[34:35], v[54:55], v[48:49]
	s_nop 0
	v_pk_mul_f32 v[36:37], v[116:117], v[34:35] op_sel:[0,1]
	v_cvt_pk_bf16_f32 v52, v34, v35
	v_pk_fma_f32 v[38:39], v[108:109], v[34:35], v[36:37] neg_lo:[0,0,1] neg_hi:[0,0,1]
	v_pk_fma_f32 v[34:35], v[108:109], v[34:35], v[36:37] op_sel_hi:[1,0,1]
	s_nop 0
	v_mov_b32_e32 v39, v35
	v_mov_b32_e32 v34, v40
	v_mov_b32_e32 v35, v56
	v_pk_add_f32 v[34:35], v[34:35], v[38:39]
	v_mov_b32_e32 v56, v41
	v_pk_mul_f32 v[36:37], v[116:117], v[34:35] op_sel:[0,1]
	v_cvt_pk_bf16_f32 v40, v34, v35
	v_pk_fma_f32 v[38:39], v[108:109], v[34:35], v[36:37] neg_lo:[0,0,1] neg_hi:[0,0,1]
	v_pk_fma_f32 v[34:35], v[108:109], v[34:35], v[36:37] op_sel_hi:[1,0,1]
	s_nop 0
	v_mov_b32_e32 v39, v35
	v_pk_add_f32 v[34:35], v[56:57], v[38:39]
	s_nop 0
	v_pk_mul_f32 v[36:37], v[116:117], v[34:35] op_sel:[0,1]
	v_cvt_pk_bf16_f32 v41, v34, v35
	v_pk_fma_f32 v[38:39], v[108:109], v[34:35], v[36:37] neg_lo:[0,0,1] neg_hi:[0,0,1]
	v_pk_fma_f32 v[34:35], v[108:109], v[34:35], v[36:37] op_sel_hi:[1,0,1]
	s_nop 0
	v_mov_b32_e32 v39, v35
	v_mov_b32_e32 v34, v42
	v_mov_b32_e32 v35, v58
	v_pk_add_f32 v[34:35], v[34:35], v[38:39]
	v_mov_b32_e32 v58, v43
	v_pk_mul_f32 v[36:37], v[116:117], v[34:35] op_sel:[0,1]
	v_cvt_pk_bf16_f32 v42, v34, v35
	v_pk_fma_f32 v[38:39], v[108:109], v[34:35], v[36:37] neg_lo:[0,0,1] neg_hi:[0,0,1]
	v_pk_fma_f32 v[34:35], v[108:109], v[34:35], v[36:37] op_sel_hi:[1,0,1]
	s_nop 0
	v_mov_b32_e32 v39, v35
	v_pk_add_f32 v[34:35], v[58:59], v[38:39]
	s_nop 0
	v_pk_mul_f32 v[36:37], v[116:117], v[34:35] op_sel:[0,1]
	v_cvt_pk_bf16_f32 v43, v34, v35
	v_pk_fma_f32 v[38:39], v[108:109], v[34:35], v[36:37] neg_lo:[0,0,1] neg_hi:[0,0,1]
	v_pk_fma_f32 v[34:35], v[108:109], v[34:35], v[36:37] op_sel_hi:[1,0,1]
	s_nop 0
	v_mov_b32_e32 v39, v35
	v_mov_b32_e32 v34, v44
	v_mov_b32_e32 v35, v60
	v_pk_add_f32 v[34:35], v[34:35], v[38:39]
	v_mov_b32_e32 v60, v45
	v_pk_mul_f32 v[36:37], v[116:117], v[34:35] op_sel:[0,1]
	v_cvt_pk_bf16_f32 v44, v34, v35
	v_pk_fma_f32 v[38:39], v[108:109], v[34:35], v[36:37] neg_lo:[0,0,1] neg_hi:[0,0,1]
	v_pk_fma_f32 v[34:35], v[108:109], v[34:35], v[36:37] op_sel_hi:[1,0,1]
	s_nop 0
	v_mov_b32_e32 v39, v35
	v_pk_add_f32 v[34:35], v[60:61], v[38:39]
	s_nop 0
	v_pk_mul_f32 v[36:37], v[116:117], v[34:35] op_sel:[0,1]
	v_cvt_pk_bf16_f32 v45, v34, v35
	v_pk_fma_f32 v[38:39], v[108:109], v[34:35], v[36:37] neg_lo:[0,0,1] neg_hi:[0,0,1]
	v_pk_fma_f32 v[34:35], v[108:109], v[34:35], v[36:37] op_sel_hi:[1,0,1]
	s_nop 0
	v_mov_b32_e32 v39, v35
	v_mov_b32_e32 v34, v46
	v_mov_b32_e32 v35, v62
	v_pk_add_f32 v[34:35], v[34:35], v[38:39]
	v_mov_b32_e32 v62, v47
	v_pk_mul_f32 v[36:37], v[116:117], v[34:35] op_sel:[0,1]
	v_cvt_pk_bf16_f32 v46, v34, v35
	v_pk_fma_f32 v[38:39], v[108:109], v[34:35], v[36:37] neg_lo:[0,0,1] neg_hi:[0,0,1]
	v_pk_fma_f32 v[34:35], v[108:109], v[34:35], v[36:37] op_sel_hi:[1,0,1]
	s_nop 0
	v_mov_b32_e32 v39, v35
	v_pk_mul_f32 v[34:35], v[118:119], v[120:121] op_sel:[0,1]
	v_pk_add_f32 v[48:49], v[62:63], v[38:39]
	v_pk_fma_f32 v[36:37], v[110:111], v[120:121], v[34:35] neg_lo:[0,0,1] neg_hi:[0,0,1]
	v_pk_fma_f32 v[34:35], v[110:111], v[120:121], v[34:35] op_sel_hi:[1,0,1]
	v_cvt_pk_bf16_f32 v47, v48, v49
	v_mov_b32_e32 v37, v35
	v_mov_b32_e32 v34, v2
	v_mov_b32_e32 v35, v18
	v_pk_add_f32 v[34:35], v[36:37], v[34:35]
	v_mov_b32_e32 v18, v3
	v_pk_mul_f32 v[36:37], v[118:119], v[34:35] op_sel:[0,1]
	v_cvt_pk_bf16_f32 v2, v34, v35
	v_pk_fma_f32 v[38:39], v[110:111], v[34:35], v[36:37] neg_lo:[0,0,1] neg_hi:[0,0,1]
	v_pk_fma_f32 v[34:35], v[110:111], v[34:35], v[36:37] op_sel_hi:[1,0,1]
	ds_write2_b32 v129, v133, v2 offset1:32
	v_mov_b32_e32 v39, v35
	v_pk_add_f32 v[2:3], v[18:19], v[38:39]
	s_nop 0
	v_cvt_pk_bf16_f32 v18, v2, v3
	ds_write2_b32 v129, v136, v18 offset0:68 offset1:100
	v_pk_mul_f32 v[18:19], v[118:119], v[2:3] op_sel:[0,1]
	s_nop 0
	v_pk_fma_f32 v[34:35], v[110:111], v[2:3], v[18:19] neg_lo:[0,0,1] neg_hi:[0,0,1]
	v_pk_fma_f32 v[2:3], v[110:111], v[2:3], v[18:19] op_sel_hi:[1,0,1]
	s_nop 0
	v_mov_b32_e32 v35, v3
	v_mov_b32_e32 v2, v4
	v_mov_b32_e32 v3, v20
	v_pk_add_f32 v[2:3], v[2:3], v[34:35]
	v_mov_b32_e32 v20, v5
	v_pk_mul_f32 v[18:19], v[118:119], v[2:3] op_sel:[0,1]
	v_cvt_pk_bf16_f32 v4, v2, v3
	v_pk_fma_f32 v[34:35], v[110:111], v[2:3], v[18:19] neg_lo:[0,0,1] neg_hi:[0,0,1]
	v_pk_fma_f32 v[2:3], v[110:111], v[2:3], v[18:19] op_sel_hi:[1,0,1]
	ds_write2_b32 v129, v137, v4 offset0:136 offset1:168
	v_mov_b32_e32 v35, v3
	v_pk_add_f32 v[2:3], v[20:21], v[34:35]
	v_add_u32_e32 v20, 0x400, v129
	v_cvt_pk_bf16_f32 v4, v2, v3
	ds_write2_b32 v129, v134, v4 offset0:204 offset1:236
	v_pk_mul_f32 v[4:5], v[118:119], v[2:3] op_sel:[0,1]
	s_nop 0
	v_pk_fma_f32 v[18:19], v[110:111], v[2:3], v[4:5] neg_lo:[0,0,1] neg_hi:[0,0,1]
	v_pk_fma_f32 v[2:3], v[110:111], v[2:3], v[4:5] op_sel_hi:[1,0,1]
	s_nop 0
	v_mov_b32_e32 v19, v3
	v_mov_b32_e32 v2, v6
	v_mov_b32_e32 v3, v22
	v_pk_add_f32 v[2:3], v[2:3], v[18:19]
	v_mov_b32_e32 v22, v7
	v_cvt_pk_bf16_f32 v4, v2, v3
	ds_write2_b32 v20, v135, v4 offset0:16 offset1:48
	v_pk_mul_f32 v[4:5], v[118:119], v[2:3] op_sel:[0,1]
	s_nop 0
	v_pk_fma_f32 v[18:19], v[110:111], v[2:3], v[4:5] neg_lo:[0,0,1] neg_hi:[0,0,1]
	v_pk_fma_f32 v[2:3], v[110:111], v[2:3], v[4:5] op_sel_hi:[1,0,1]
	s_nop 0
	v_mov_b32_e32 v19, v3
	v_pk_add_f32 v[2:3], v[22:23], v[18:19]
	s_nop 0
	v_cvt_pk_bf16_f32 v4, v2, v3
	ds_write2_b32 v20, v50, v4 offset0:84 offset1:116
	v_pk_mul_f32 v[4:5], v[118:119], v[2:3] op_sel:[0,1]
	s_nop 0
	v_pk_fma_f32 v[6:7], v[110:111], v[2:3], v[4:5] neg_lo:[0,0,1] neg_hi:[0,0,1]
	v_pk_fma_f32 v[2:3], v[110:111], v[2:3], v[4:5] op_sel_hi:[1,0,1]
	s_nop 0
	v_mov_b32_e32 v7, v3
	v_mov_b32_e32 v2, v8
	v_mov_b32_e32 v3, v24
	v_pk_add_f32 v[2:3], v[2:3], v[6:7]
	v_mov_b32_e32 v24, v9
	v_cvt_pk_bf16_f32 v4, v2, v3
	ds_write2_b32 v20, v51, v4 offset0:152 offset1:184
	v_pk_mul_f32 v[4:5], v[118:119], v[2:3] op_sel:[0,1]
	v_add_u32_e32 v8, 0x800, v129
	v_pk_fma_f32 v[6:7], v[110:111], v[2:3], v[4:5] neg_lo:[0,0,1] neg_hi:[0,0,1]
	v_pk_fma_f32 v[2:3], v[110:111], v[2:3], v[4:5] op_sel_hi:[1,0,1]
	s_nop 0
	v_mov_b32_e32 v7, v3
	v_pk_add_f32 v[2:3], v[24:25], v[6:7]
	s_nop 0
	v_cvt_pk_bf16_f32 v4, v2, v3
	ds_write2_b32 v20, v52, v4 offset0:220 offset1:252
	v_pk_mul_f32 v[4:5], v[118:119], v[2:3] op_sel:[0,1]
	s_nop 0
	v_pk_fma_f32 v[6:7], v[110:111], v[2:3], v[4:5] neg_lo:[0,0,1] neg_hi:[0,0,1]
	v_pk_fma_f32 v[2:3], v[110:111], v[2:3], v[4:5] op_sel_hi:[1,0,1]
	s_nop 0
	v_mov_b32_e32 v7, v3
	v_mov_b32_e32 v2, v10
	v_mov_b32_e32 v3, v26
	v_pk_add_f32 v[2:3], v[2:3], v[6:7]
	v_mov_b32_e32 v26, v11
	v_cvt_pk_bf16_f32 v4, v2, v3
	ds_write2_b32 v8, v40, v4 offset0:32 offset1:64
	v_pk_mul_f32 v[4:5], v[118:119], v[2:3] op_sel:[0,1]
	s_nop 0
	v_pk_fma_f32 v[6:7], v[110:111], v[2:3], v[4:5] neg_lo:[0,0,1] neg_hi:[0,0,1]
	v_pk_fma_f32 v[2:3], v[110:111], v[2:3], v[4:5] op_sel_hi:[1,0,1]
	s_nop 0
	v_mov_b32_e32 v7, v3
	v_pk_add_f32 v[2:3], v[26:27], v[6:7]
	s_nop 0
	v_cvt_pk_bf16_f32 v4, v2, v3
	ds_write2_b32 v8, v41, v4 offset0:100 offset1:132
	v_pk_mul_f32 v[4:5], v[118:119], v[2:3] op_sel:[0,1]
	s_nop 0
	v_pk_fma_f32 v[6:7], v[110:111], v[2:3], v[4:5] neg_lo:[0,0,1] neg_hi:[0,0,1]
	v_pk_fma_f32 v[2:3], v[110:111], v[2:3], v[4:5] op_sel_hi:[1,0,1]
	s_nop 0
	v_mov_b32_e32 v7, v3
	v_mov_b32_e32 v2, v12
	v_mov_b32_e32 v3, v28
	v_pk_add_f32 v[2:3], v[2:3], v[6:7]
	v_mov_b32_e32 v28, v13
	v_cvt_pk_bf16_f32 v4, v2, v3
	ds_write2_b32 v8, v42, v4 offset0:168 offset1:200
	v_pk_mul_f32 v[4:5], v[118:119], v[2:3] op_sel:[0,1]
	v_add_u32_e32 v8, 0xc00, v129
	v_pk_fma_f32 v[6:7], v[110:111], v[2:3], v[4:5] neg_lo:[0,0,1] neg_hi:[0,0,1]
	v_pk_fma_f32 v[2:3], v[110:111], v[2:3], v[4:5] op_sel_hi:[1,0,1]
	v_add_u32_e32 v5, 0xa00, v129
	v_mov_b32_e32 v7, v3
	v_pk_add_f32 v[2:3], v[28:29], v[6:7]
	s_nop 0
	v_cvt_pk_bf16_f32 v4, v2, v3
	ds_write2_b32 v5, v43, v4 offset0:108 offset1:140
	v_pk_mul_f32 v[4:5], v[118:119], v[2:3] op_sel:[0,1]
	s_nop 0
	v_pk_fma_f32 v[6:7], v[110:111], v[2:3], v[4:5] neg_lo:[0,0,1] neg_hi:[0,0,1]
	v_pk_fma_f32 v[2:3], v[110:111], v[2:3], v[4:5] op_sel_hi:[1,0,1]
	s_nop 0
	v_mov_b32_e32 v7, v3
	v_mov_b32_e32 v2, v14
	v_mov_b32_e32 v3, v30
	v_pk_add_f32 v[2:3], v[2:3], v[6:7]
	v_mov_b32_e32 v30, v15
	v_cvt_pk_bf16_f32 v4, v2, v3
	ds_write2_b32 v8, v44, v4 offset0:48 offset1:80
	v_pk_mul_f32 v[4:5], v[118:119], v[2:3] op_sel:[0,1]
	v_add_u32_e32 v14, s13, v100
	v_pk_fma_f32 v[6:7], v[110:111], v[2:3], v[4:5] neg_lo:[0,0,1] neg_hi:[0,0,1]
	v_pk_fma_f32 v[2:3], v[110:111], v[2:3], v[4:5] op_sel_hi:[1,0,1]
	v_ashrrev_i32_e32 v15, 31, v14
	v_mov_b32_e32 v7, v3
	v_pk_add_f32 v[2:3], v[30:31], v[6:7]
	v_add_u32_e32 v10, 1, v14
	v_cvt_pk_bf16_f32 v4, v2, v3
	ds_write2_b32 v8, v45, v4 offset0:116 offset1:148
	v_pk_mul_f32 v[4:5], v[118:119], v[2:3] op_sel:[0,1]
	v_ashrrev_i32_e32 v11, 31, v10
	v_pk_fma_f32 v[6:7], v[110:111], v[2:3], v[4:5] neg_lo:[0,0,1] neg_hi:[0,0,1]
	v_pk_fma_f32 v[2:3], v[110:111], v[2:3], v[4:5] op_sel_hi:[1,0,1]
	v_lshlrev_b64 v[18:19], 10, v[10:11]
	v_mov_b32_e32 v7, v3
	v_mov_b32_e32 v2, v16
	v_mov_b32_e32 v3, v32
	v_pk_add_f32 v[2:3], v[2:3], v[6:7]
	v_mov_b32_e32 v32, v17
	v_cvt_pk_bf16_f32 v4, v2, v3
	ds_write2_b32 v8, v46, v4 offset0:184 offset1:216
	v_pk_mul_f32 v[4:5], v[118:119], v[2:3] op_sel:[0,1]
	v_lshlrev_b64 v[16:17], 10, v[14:15]
	v_pk_fma_f32 v[6:7], v[110:111], v[2:3], v[4:5] neg_lo:[0,0,1] neg_hi:[0,0,1]
	v_pk_fma_f32 v[2:3], v[110:111], v[2:3], v[4:5] op_sel_hi:[1,0,1]
	v_or_b32_e32 v16, v16, v112
	v_mov_b32_e32 v7, v3
	v_pk_add_f32 v[120:121], v[32:33], v[6:7]
	v_add_u32_e32 v3, 0xe00, v129
	v_cvt_pk_bf16_f32 v2, v120, v121
	ds_write2_b32 v3, v47, v2 offset0:124 offset1:156
	s_waitcnt lgkmcnt(0)
	v_lshl_add_u64 v[2:3], v[16:17], 2, s[66:67]
	ds_read_b128 v[2:5], v130
	ds_read_b128 v[6:9], v130 offset:64
	v_or_b32_e32 v18, v18, v112
	s_waitcnt lgkmcnt(1)
	v_mfma_f32_16x16x32_bf16 v[2:5], v[2:5], v[80:83], 0
	v_lshl_add_u64 v[10:11], v[18:19], 2, s[66:67]
	s_add_i32 s13, s13, 16
	s_waitcnt lgkmcnt(0)
	v_mfma_f32_16x16x32_bf16 v[2:5], v[6:9], v[84:87], v[2:5]
	ds_read_b128 v[6:9], v130 offset:128
	ds_read_b128 v[10:13], v130 offset:192
	s_cmpk_eq_i32 s13, 0x80
	s_waitcnt lgkmcnt(1)
	v_mfma_f32_16x16x32_bf16 v[2:5], v[6:9], v[88:91], v[2:5]
	v_add_u32_e32 v6, 2, v14
	v_ashrrev_i32_e32 v7, 31, v6
	v_lshlrev_b64 v[22:23], 10, v[6:7]
	v_or_b32_e32 v22, v22, v112
	v_lshl_add_u64 v[6:7], v[22:23], 2, s[66:67]
	v_add_u32_e32 v6, 3, v14
	v_ashrrev_i32_e32 v7, 31, v6
	v_lshlrev_b64 v[24:25], 10, v[6:7]
	v_or_b32_e32 v24, v24, v112
	v_lshl_add_u64 v[6:7], v[24:25], 2, s[66:67]
	v_add_u32_e32 v6, 0x80, v14
	s_waitcnt lgkmcnt(0)
	v_mfma_f32_16x16x32_bf16 v[2:5], v[10:13], v[92:95], v[2:5]
	v_ashrrev_i32_e32 v7, 31, v6
	v_add_u32_e32 v8, 0x81, v14
	v_add_u32_e32 v10, 0x82, v14
	v_add_u32_e32 v12, 0x83, v14
	v_lshlrev_b64 v[26:27], 10, v[6:7]
	v_ashrrev_i32_e32 v9, 31, v8
	v_ashrrev_i32_e32 v11, 31, v10
	v_ashrrev_i32_e32 v13, 31, v12
	v_or_b32_e32 v26, v26, v112
	v_lshlrev_b64 v[28:29], 10, v[8:9]
	v_lshlrev_b64 v[30:31], 10, v[10:11]
	v_lshlrev_b64 v[32:33], 10, v[12:13]
	v_lshl_add_u64 v[6:7], v[26:27], 2, s[66:67]
	v_or_b32_e32 v28, v28, v112
	v_or_b32_e32 v30, v30, v112
	v_or_b32_e32 v32, v32, v112
	v_lshl_add_u64 v[8:9], v[28:29], 2, s[66:67]
	v_lshl_add_u64 v[10:11], v[30:31], 2, s[66:67]
	v_lshl_add_u64 v[12:13], v[32:33], 2, s[66:67]
	ds_read_b128 v[10:13], v130 offset:4416
	s_waitcnt vmcnt(7)
	v_fma_f32 v2, v131, v156, v2
	v_mul_f32_e32 v6, 0x3d372713, v2
	v_mul_f32_e32 v6, v2, v6
	v_fma_f32 v6, v2, v6, v2
	v_mul_f32_e32 v6, 0x3f4c422a, v6
	v_add_f32_e32 v6, v6, v6
	v_mul_f32_e32 v6, 0x3fb8aa3b, v6
	v_exp_f32_e32 v6, v6
	s_waitcnt vmcnt(6)
	v_fma_f32 v7, v131, v157, v3
	v_mul_f32_e32 v3, 0x3d372713, v7
	v_mul_f32_e32 v3, v7, v3
	v_fma_f32 v3, v7, v3, v7
	v_add_f32_e32 v6, 1.0, v6
	v_mul_f32_e32 v3, 0x3f4c422a, v3
	v_rcp_f32_e32 v6, v6
	v_add_f32_e32 v3, v3, v3
	v_mul_f32_e32 v3, 0x3fb8aa3b, v3
	v_exp_f32_e32 v3, v3
	v_fma_f32 v6, v6, -2.0, 1.0
	v_mul_f32_e32 v2, 0.5, v2
	v_add_f32_e32 v6, 1.0, v6
	v_mul_f32_e32 v2, v2, v6
	v_add_f32_e32 v3, 1.0, v3
	v_rcp_f32_e32 v6, v3
	v_cvt_pk_bf16_f32 v8, v2, s0
	v_lshl_add_u64 v[2:3], v[16:17], 1, s[68:69]
	s_waitcnt vmcnt(5)
	v_fma_f32 v4, v131, v158, v4
	global_store_short v[2:3], v8, off
	v_mul_f32_e32 v3, 0x3d372713, v4
	v_mul_f32_e32 v3, v4, v3
	v_fma_f32 v3, v4, v3, v4
	v_mul_f32_e32 v3, 0x3f4c422a, v3
	v_add_f32_e32 v3, v3, v3
	v_mul_f32_e32 v3, 0x3fb8aa3b, v3
	v_exp_f32_e32 v3, v3
	v_fma_f32 v2, v6, -2.0, 1.0
	v_mul_f32_e32 v6, 0.5, v7
	v_add_f32_e32 v2, 1.0, v2
	v_add_f32_e32 v3, 1.0, v3
	v_mul_f32_e32 v2, v6, v2
	v_rcp_f32_e32 v6, v3
	v_cvt_pk_bf16_f32 v7, v2, s0
	v_lshl_add_u64 v[2:3], v[18:19], 1, s[68:69]
	global_store_short v[2:3], v7, off
	v_fma_f32 v2, v6, -2.0, 1.0
	ds_read_b128 v[6:9], v130 offset:4352
	ds_read_b128 v[14:17], v130 offset:4480
	ds_read_b128 v[18:21], v130 offset:4544
	s_waitcnt lgkmcnt(2)
	v_mfma_f32_16x16x32_bf16 v[6:9], v[6:9], v[80:83], 0
	v_mul_f32_e32 v3, 0.5, v4
	v_add_f32_e32 v2, 1.0, v2
	s_waitcnt vmcnt(6)
	v_fmac_f32_e32 v5, v131, v159
	v_mul_f32_e32 v2, v3, v2
	v_mul_f32_e32 v3, 0x3d372713, v5
	v_mfma_f32_16x16x32_bf16 v[6:9], v[10:13], v[84:87], v[6:9]
	v_mul_f32_e32 v3, v5, v3
	v_fma_f32 v3, v5, v3, v5
	v_mul_f32_e32 v3, 0x3f4c422a, v3
	v_add_f32_e32 v3, v3, v3
	s_waitcnt lgkmcnt(1)
	v_mfma_f32_16x16x32_bf16 v[6:9], v[14:17], v[88:91], v[6:9]
	v_mul_f32_e32 v3, 0x3fb8aa3b, v3
	v_exp_f32_e32 v3, v3
	v_cvt_pk_bf16_f32 v4, v2, s0
	s_waitcnt lgkmcnt(0)
	v_mfma_f32_16x16x32_bf16 v[6:9], v[18:21], v[92:95], v[6:9]
	v_mul_f32_e32 v5, 0.5, v5
	v_add_f32_e32 v2, 1.0, v3
	v_rcp_f32_e32 v10, v2
	v_lshl_add_u64 v[2:3], v[22:23], 1, s[68:69]
	global_store_short v[2:3], v4, off
	s_waitcnt vmcnt(6)
	s_nop 1
	v_fma_f32 v4, v131, v160, v6
	v_mul_f32_e32 v3, 0x3d372713, v4
	v_mul_f32_e32 v3, v4, v3
	v_fma_f32 v3, v4, v3, v4
	v_mul_f32_e32 v3, 0x3f4c422a, v3
	v_add_f32_e32 v3, v3, v3
	v_mul_f32_e32 v3, 0x3fb8aa3b, v3
	v_exp_f32_e32 v3, v3
	v_fma_f32 v2, v10, -2.0, 1.0
	v_add_f32_e32 v2, 1.0, v2
	v_mul_f32_e32 v2, v5, v2
	v_add_f32_e32 v3, 1.0, v3
	v_rcp_f32_e32 v5, v3
	v_cvt_pk_bf16_f32 v6, v2, s0
	v_lshl_add_u64 v[2:3], v[24:25], 1, s[68:69]
	global_store_short v[2:3], v6, off
	v_fma_f32 v2, v5, -2.0, 1.0
	s_waitcnt vmcnt(6)
	v_fma_f32 v5, v131, v161, v7
	v_mul_f32_e32 v3, 0x3d372713, v5
	v_mul_f32_e32 v3, v5, v3
	v_fma_f32 v3, v5, v3, v5
	v_mul_f32_e32 v3, 0x3f4c422a, v3
	v_add_f32_e32 v3, v3, v3
	v_mul_f32_e32 v3, 0x3fb8aa3b, v3
	v_exp_f32_e32 v3, v3
	v_mul_f32_e32 v4, 0.5, v4
	v_add_f32_e32 v2, 1.0, v2
	v_mul_f32_e32 v2, v4, v2
	v_add_f32_e32 v3, 1.0, v3
	v_rcp_f32_e32 v4, v3
	v_cvt_pk_bf16_f32 v6, v2, s0
	v_lshl_add_u64 v[2:3], v[26:27], 1, s[68:69]
	global_store_short v[2:3], v6, off
	v_fma_f32 v2, v4, -2.0, 1.0
	s_waitcnt vmcnt(6)
	v_fma_f32 v4, v131, v162, v8
	v_mul_f32_e32 v3, 0x3d372713, v4
	v_mul_f32_e32 v3, v4, v3
	v_fma_f32 v3, v4, v3, v4
	v_mul_f32_e32 v3, 0x3f4c422a, v3
	v_add_f32_e32 v3, v3, v3
	v_mul_f32_e32 v3, 0x3fb8aa3b, v3
	v_exp_f32_e32 v3, v3
	v_mul_f32_e32 v5, 0.5, v5
	v_add_f32_e32 v2, 1.0, v2
	v_mul_f32_e32 v2, v5, v2
	v_add_f32_e32 v3, 1.0, v3
	v_rcp_f32_e32 v5, v3
	v_cvt_pk_bf16_f32 v6, v2, s0
	v_lshl_add_u64 v[2:3], v[28:29], 1, s[68:69]
	s_waitcnt vmcnt(5)
	v_fmac_f32_e32 v9, v131, v163
	global_store_short v[2:3], v6, off
	v_mul_f32_e32 v3, 0x3d372713, v9
	v_mul_f32_e32 v3, v9, v3
	v_fma_f32 v3, v9, v3, v9
	v_mul_f32_e32 v3, 0x3f4c422a, v3
	v_add_f32_e32 v3, v3, v3
	v_mul_f32_e32 v3, 0x3fb8aa3b, v3
	v_exp_f32_e32 v3, v3
	v_fma_f32 v2, v5, -2.0, 1.0
	v_mul_f32_e32 v4, 0.5, v4
	v_add_f32_e32 v2, 1.0, v2
	v_add_f32_e32 v3, 1.0, v3
	v_mul_f32_e32 v2, v4, v2
	v_rcp_f32_e32 v4, v3
	v_cvt_pk_bf16_f32 v5, v2, s0
	v_lshl_add_u64 v[2:3], v[30:31], 1, s[68:69]
	global_store_short v[2:3], v5, off
	v_fma_f32 v2, v4, -2.0, 1.0
	v_mul_f32_e32 v3, 0.5, v9
	v_add_f32_e32 v2, 1.0, v2
	v_mul_f32_e32 v2, v3, v2
	v_mov_b64_e32 v[18:19], v[96:97]
	v_cvt_pk_bf16_f32 v4, v2, s0
	v_lshl_add_u64 v[2:3], v[32:33], 1, s[68:69]
	v_mov_b64_e32 v[20:21], v[98:99]
	global_store_short v[2:3], v4, off
	s_cbranch_scc1 .LBB0_1712

.LBB0_2054:
	v_mbcnt_lo_u32_b32 v148, -1, 0
	v_mbcnt_hi_u32_b32 v148, -1, v148
	v_xor_b32_e32 v149, 32, v148
	v_lshlrev_b32_e32 v149, 2, v149
	v_mov_b32_e32 v150, 0x3727c5ac
	v_lshlrev_b32_e32 v151, 3, v148
	global_load_dwordx4 v[64:67], v[2:3], off
	global_load_dwordx4 v[68:71], v[2:3], off offset:1024
	global_load_dwordx4 v[72:75], v[2:3], off offset:2048
	global_load_dwordx4 v[76:79], v[2:3], off offset:3072
	global_load_dwordx4 v[80:83], v[4:5], off
	global_load_dwordx4 v[84:87], v[4:5], off offset:1024
	global_load_dwordx4 v[88:91], v[4:5], off offset:2048
	global_load_dwordx4 v[92:95], v[4:5], off offset:3072
	v_ashrrev_i32_e32 v159, 31, v8
	v_mov_b32_e32 v158, v8
	v_lshlrev_b64 v[158:159], 12, v[158:159]
	v_lshl_add_u64 v[152:153], v[0:1], 0, v[158:159]
	global_load_dwordx4 v[96:99], v[152:153], off
	global_load_dwordx4 v[100:103], v[152:153], off offset:1024
	global_load_dwordx4 v[104:107], v[152:153], off offset:2048
	global_load_dwordx4 v[108:111], v[152:153], off offset:3072
	s_add_i32 s99, s92, s96
	s_cmpk_lt_i32 s99, 0x800
	s_cselect_b32 s99, s0, 0
	v_add_u32_e32 v156, s99, v8
	v_ashrrev_i32_e32 v159, 31, v156
	v_mov_b32_e32 v158, v156
	v_lshlrev_b64 v[158:159], 12, v[158:159]
	v_lshl_add_u64 v[154:155], v[0:1], 0, v[158:159]
	global_load_dwordx4 v[112:115], v[154:155], off
	global_load_dwordx4 v[116:119], v[154:155], off offset:1024
	global_load_dwordx4 v[120:123], v[154:155], off offset:2048
	global_load_dwordx4 v[124:127], v[154:155], off offset:3072
	s_waitcnt vmcnt(4)
	s_branch .Lln_p18_procA
.Lln_p18_loopA:
	s_add_i32 s99, s92, s96
	s_cmpk_lt_i32 s99, 0x800
	s_cselect_b32 s99, s0, 0
	v_add_u32_e32 v156, s99, v8
	v_ashrrev_i32_e32 v159, 31, v156
	v_mov_b32_e32 v158, v156
	v_lshlrev_b64 v[158:159], 12, v[158:159]
	v_lshl_add_u64 v[154:155], v[0:1], 0, v[158:159]
	global_load_dwordx4 v[112:115], v[154:155], off
	global_load_dwordx4 v[116:119], v[154:155], off offset:1024
	global_load_dwordx4 v[120:123], v[154:155], off offset:2048
	global_load_dwordx4 v[124:127], v[154:155], off offset:3072
	s_waitcnt vmcnt(8)
.Lln_p18_procA:
	v_add_f32_e32 v128, v96, v97
	v_add_f32_e32 v129, v100, v101
	v_add_f32_e32 v130, v104, v105
	v_add_f32_e32 v131, v108, v109
	v_add_f32_e32 v128, v98, v128
	v_add_f32_e32 v129, v102, v129
	v_add_f32_e32 v130, v106, v130
	v_add_f32_e32 v131, v110, v131
	v_add_f32_e32 v128, v99, v128
	v_add_f32_e32 v129, v103, v129
	v_add_f32_e32 v130, v107, v130
	v_add_f32_e32 v131, v111, v131
	v_add_f32_e32 v132, v128, v129
	v_add_f32_e32 v132, v132, v130
	v_add_f32_e32 v132, v132, v131
	s_nop 1
	v_add_f32_dpp v132, v132, v132 quad_perm:[1,0,3,2] row_mask:0xf bank_mask:0xf
	s_nop 1
	v_add_f32_dpp v132, v132, v132 quad_perm:[2,3,0,1] row_mask:0xf bank_mask:0xf
	s_nop 1
	v_add_f32_dpp v132, v132, v132 row_half_mirror row_mask:0xf bank_mask:0xf
	s_nop 1
	v_add_f32_dpp v132, v132, v132 row_mirror row_mask:0xf bank_mask:0xf
	ds_swizzle_b32 v147, v132 offset:0x401f
	s_waitcnt lgkmcnt(0)
	v_add_f32_e32 v132, v132, v147
	ds_bpermute_b32 v147, v149, v132
	s_waitcnt lgkmcnt(0)
	v_add_f32_e32 v132, v132, v147
	v_mul_f32_e32 v133, 0x3a800000, v132
	v_sub_f32_e32 v96, v96, v133
	v_sub_f32_e32 v97, v97, v133
	v_sub_f32_e32 v98, v98, v133
	v_sub_f32_e32 v99, v99, v133
	v_sub_f32_e32 v100, v100, v133
	v_sub_f32_e32 v101, v101, v133
	v_sub_f32_e32 v102, v102, v133
	v_sub_f32_e32 v103, v103, v133
	v_sub_f32_e32 v104, v104, v133
	v_sub_f32_e32 v105, v105, v133
	v_sub_f32_e32 v106, v106, v133
	v_sub_f32_e32 v107, v107, v133
	v_sub_f32_e32 v108, v108, v133
	v_sub_f32_e32 v109, v109, v133
	v_sub_f32_e32 v110, v110, v133
	v_sub_f32_e32 v111, v111, v133
	v_mul_f32_e32 v134, v96, v96
	v_mul_f32_e32 v135, v97, v97
	v_add_f32_e32 v134, v134, v135
	v_mul_f32_e32 v135, v98, v98
	v_add_f32_e32 v134, v135, v134
	v_mul_f32_e32 v135, v99, v99
	v_add_f32_e32 v134, v135, v134
	v_mul_f32_e32 v135, v100, v100
	v_add_f32_e32 v134, v135, v134
	v_mul_f32_e32 v135, v101, v101
	v_add_f32_e32 v134, v135, v134
	v_mul_f32_e32 v135, v102, v102
	v_add_f32_e32 v134, v135, v134
	v_mul_f32_e32 v135, v103, v103
	v_add_f32_e32 v134, v135, v134
	v_mul_f32_e32 v135, v104, v104
	v_add_f32_e32 v134, v135, v134
	v_mul_f32_e32 v135, v105, v105
	v_add_f32_e32 v134, v135, v134
	v_mul_f32_e32 v135, v106, v106
	v_add_f32_e32 v134, v135, v134
	v_mul_f32_e32 v135, v107, v107
	v_add_f32_e32 v134, v135, v134
	v_mul_f32_e32 v135, v108, v108
	v_add_f32_e32 v134, v135, v134
	v_mul_f32_e32 v135, v109, v109
	v_add_f32_e32 v134, v135, v134
	v_mul_f32_e32 v135, v110, v110
	v_add_f32_e32 v134, v135, v134
	v_mul_f32_e32 v135, v111, v111
	v_add_f32_e32 v134, v135, v134
	s_nop 1
	v_add_f32_dpp v134, v134, v134 quad_perm:[1,0,3,2] row_mask:0xf bank_mask:0xf
	s_nop 1
	v_add_f32_dpp v134, v134, v134 quad_perm:[2,3,0,1] row_mask:0xf bank_mask:0xf
	s_nop 1
	v_add_f32_dpp v134, v134, v134 row_half_mirror row_mask:0xf bank_mask:0xf
	s_nop 1
	v_add_f32_dpp v134, v134, v134 row_mirror row_mask:0xf bank_mask:0xf
	ds_swizzle_b32 v147, v134 offset:0x401f
	s_waitcnt lgkmcnt(0)
	v_add_f32_e32 v134, v134, v147
	ds_bpermute_b32 v147, v149, v134
	s_waitcnt lgkmcnt(0)
	v_add_f32_e32 v134, v134, v147
	v_fmamk_f32 v134, v134, 0x3a800000, v150
	v_rsq_f32_e32 v134, v134
	s_nop 0
	v_mul_f32_e32 v96, v96, v134
	v_mul_f32_e32 v97, v97, v134
	v_mul_f32_e32 v98, v98, v134
	v_mul_f32_e32 v99, v99, v134
	v_mul_f32_e32 v100, v100, v134
	v_mul_f32_e32 v101, v101, v134
	v_mul_f32_e32 v102, v102, v134
	v_mul_f32_e32 v103, v103, v134
	v_mul_f32_e32 v104, v104, v134
	v_mul_f32_e32 v105, v105, v134
	v_mul_f32_e32 v106, v106, v134
	v_mul_f32_e32 v107, v107, v134
	v_mul_f32_e32 v108, v108, v134
	v_mul_f32_e32 v109, v109, v134
	v_mul_f32_e32 v110, v110, v134
	v_mul_f32_e32 v111, v111, v134
	v_fma_f32 v96, v64, v96, v80
	v_fma_f32 v97, v65, v97, v81
	v_fma_f32 v98, v66, v98, v82
	v_fma_f32 v99, v67, v99, v83
	v_fma_f32 v100, v68, v100, v84
	v_fma_f32 v101, v69, v101, v85
	v_fma_f32 v102, v70, v102, v86
	v_fma_f32 v103, v71, v103, v87
	v_fma_f32 v104, v72, v104, v88
	v_fma_f32 v105, v73, v105, v89
	v_fma_f32 v106, v74, v106, v90
	v_fma_f32 v107, v75, v107, v91
	v_fma_f32 v108, v76, v108, v92
	v_fma_f32 v109, v77, v109, v93
	v_fma_f32 v110, v78, v110, v94
	v_fma_f32 v111, v79, v111, v95
	v_ashrrev_i32_e32 v159, 31, v8
	v_mov_b32_e32 v158, v8
	v_lshlrev_b64 v[158:159], 12, v[158:159]
	v_lshl_add_u64 v[160:161], s[60:61], 0, v[158:159]
	v_lshlrev_b32_e32 v158, 4, v148
	v_mov_b32_e32 v159, 0
	v_lshl_add_u64 v[160:161], v[160:161], 0, v[158:159]
	global_store_dwordx4 v[160:161], v[96:99], off
	global_store_dwordx4 v[160:161], v[100:103], off offset:1024
	global_store_dwordx4 v[160:161], v[104:107], off offset:2048
	global_store_dwordx4 v[160:161], v[108:111], off offset:3072
	v_mov_b32_e32 v8, v156
	v_mov_b32_e32 v152, v154
	v_mov_b32_e32 v153, v155
	s_add_i32 s92, s92, s96
	s_cmpk_lt_i32 s92, 0x800
	s_cbranch_scc0 .LBB0_2055
	s_add_i32 s99, s92, s96
	s_cmpk_lt_i32 s99, 0x800
	s_cselect_b32 s99, s0, 0
	v_add_u32_e32 v156, s99, v8
	v_ashrrev_i32_e32 v159, 31, v156
	v_mov_b32_e32 v158, v156
	v_lshlrev_b64 v[158:159], 12, v[158:159]
	v_lshl_add_u64 v[154:155], v[0:1], 0, v[158:159]
	global_load_dwordx4 v[96:99], v[154:155], off
	global_load_dwordx4 v[100:103], v[154:155], off offset:1024
	global_load_dwordx4 v[104:107], v[154:155], off offset:2048
	global_load_dwordx4 v[108:111], v[154:155], off offset:3072
	s_waitcnt vmcnt(8)
	v_add_f32_e32 v128, v112, v113
	v_add_f32_e32 v129, v116, v117
	v_add_f32_e32 v130, v120, v121
	v_add_f32_e32 v131, v124, v125
	v_add_f32_e32 v128, v114, v128
	v_add_f32_e32 v129, v118, v129
	v_add_f32_e32 v130, v122, v130
	v_add_f32_e32 v131, v126, v131
	v_add_f32_e32 v128, v115, v128
	v_add_f32_e32 v129, v119, v129
	v_add_f32_e32 v130, v123, v130
	v_add_f32_e32 v131, v127, v131
	v_add_f32_e32 v132, v128, v129
	v_add_f32_e32 v132, v132, v130
	v_add_f32_e32 v132, v132, v131
	s_nop 1
	v_add_f32_dpp v132, v132, v132 quad_perm:[1,0,3,2] row_mask:0xf bank_mask:0xf
	s_nop 1
	v_add_f32_dpp v132, v132, v132 quad_perm:[2,3,0,1] row_mask:0xf bank_mask:0xf
	s_nop 1
	v_add_f32_dpp v132, v132, v132 row_half_mirror row_mask:0xf bank_mask:0xf
	s_nop 1
	v_add_f32_dpp v132, v132, v132 row_mirror row_mask:0xf bank_mask:0xf
	ds_swizzle_b32 v147, v132 offset:0x401f
	s_waitcnt lgkmcnt(0)
	v_add_f32_e32 v132, v132, v147
	ds_bpermute_b32 v147, v149, v132
	s_waitcnt lgkmcnt(0)
	v_add_f32_e32 v132, v132, v147
	v_mul_f32_e32 v133, 0x3a800000, v132
	v_sub_f32_e32 v112, v112, v133
	v_sub_f32_e32 v113, v113, v133
	v_sub_f32_e32 v114, v114, v133
	v_sub_f32_e32 v115, v115, v133
	v_sub_f32_e32 v116, v116, v133
	v_sub_f32_e32 v117, v117, v133
	v_sub_f32_e32 v118, v118, v133
	v_sub_f32_e32 v119, v119, v133
	v_sub_f32_e32 v120, v120, v133
	v_sub_f32_e32 v121, v121, v133
	v_sub_f32_e32 v122, v122, v133
	v_sub_f32_e32 v123, v123, v133
	v_sub_f32_e32 v124, v124, v133
	v_sub_f32_e32 v125, v125, v133
	v_sub_f32_e32 v126, v126, v133
	v_sub_f32_e32 v127, v127, v133
	v_mul_f32_e32 v134, v112, v112
	v_mul_f32_e32 v135, v113, v113
	v_add_f32_e32 v134, v134, v135
	v_mul_f32_e32 v135, v114, v114
	v_add_f32_e32 v134, v135, v134
	v_mul_f32_e32 v135, v115, v115
	v_add_f32_e32 v134, v135, v134
	v_mul_f32_e32 v135, v116, v116
	v_add_f32_e32 v134, v135, v134
	v_mul_f32_e32 v135, v117, v117
	v_add_f32_e32 v134, v135, v134
	v_mul_f32_e32 v135, v118, v118
	v_add_f32_e32 v134, v135, v134
	v_mul_f32_e32 v135, v119, v119
	v_add_f32_e32 v134, v135, v134
	v_mul_f32_e32 v135, v120, v120
	v_add_f32_e32 v134, v135, v134
	v_mul_f32_e32 v135, v121, v121
	v_add_f32_e32 v134, v135, v134
	v_mul_f32_e32 v135, v122, v122
	v_add_f32_e32 v134, v135, v134
	v_mul_f32_e32 v135, v123, v123
	v_add_f32_e32 v134, v135, v134
	v_mul_f32_e32 v135, v124, v124
	v_add_f32_e32 v134, v135, v134
	v_mul_f32_e32 v135, v125, v125
	v_add_f32_e32 v134, v135, v134
	v_mul_f32_e32 v135, v126, v126
	v_add_f32_e32 v134, v135, v134
	v_mul_f32_e32 v135, v127, v127
	v_add_f32_e32 v134, v135, v134
	s_nop 1
	v_add_f32_dpp v134, v134, v134 quad_perm:[1,0,3,2] row_mask:0xf bank_mask:0xf
	s_nop 1
	v_add_f32_dpp v134, v134, v134 quad_perm:[2,3,0,1] row_mask:0xf bank_mask:0xf
	s_nop 1
	v_add_f32_dpp v134, v134, v134 row_half_mirror row_mask:0xf bank_mask:0xf
	s_nop 1
	v_add_f32_dpp v134, v134, v134 row_mirror row_mask:0xf bank_mask:0xf
	ds_swizzle_b32 v147, v134 offset:0x401f
	s_waitcnt lgkmcnt(0)
	v_add_f32_e32 v134, v134, v147
	ds_bpermute_b32 v147, v149, v134
	s_waitcnt lgkmcnt(0)
	v_add_f32_e32 v134, v134, v147
	v_fmamk_f32 v134, v134, 0x3a800000, v150
	v_rsq_f32_e32 v134, v134
	s_nop 0
	v_mul_f32_e32 v112, v112, v134
	v_mul_f32_e32 v113, v113, v134
	v_mul_f32_e32 v114, v114, v134
	v_mul_f32_e32 v115, v115, v134
	v_mul_f32_e32 v116, v116, v134
	v_mul_f32_e32 v117, v117, v134
	v_mul_f32_e32 v118, v118, v134
	v_mul_f32_e32 v119, v119, v134
	v_mul_f32_e32 v120, v120, v134
	v_mul_f32_e32 v121, v121, v134
	v_mul_f32_e32 v122, v122, v134
	v_mul_f32_e32 v123, v123, v134
	v_mul_f32_e32 v124, v124, v134
	v_mul_f32_e32 v125, v125, v134
	v_mul_f32_e32 v126, v126, v134
	v_mul_f32_e32 v127, v127, v134
	v_fma_f32 v112, v64, v112, v80
	v_fma_f32 v113, v65, v113, v81
	v_fma_f32 v114, v66, v114, v82
	v_fma_f32 v115, v67, v115, v83
	v_fma_f32 v116, v68, v116, v84
	v_fma_f32 v117, v69, v117, v85
	v_fma_f32 v118, v70, v118, v86
	v_fma_f32 v119, v71, v119, v87
	v_fma_f32 v120, v72, v120, v88
	v_fma_f32 v121, v73, v121, v89
	v_fma_f32 v122, v74, v122, v90
	v_fma_f32 v123, v75, v123, v91
	v_fma_f32 v124, v76, v124, v92
	v_fma_f32 v125, v77, v125, v93
	v_fma_f32 v126, v78, v126, v94
	v_fma_f32 v127, v79, v127, v95
	v_ashrrev_i32_e32 v159, 31, v8
	v_mov_b32_e32 v158, v8
	v_lshlrev_b64 v[158:159], 12, v[158:159]
	v_lshl_add_u64 v[160:161], s[60:61], 0, v[158:159]
	v_lshlrev_b32_e32 v158, 4, v148
	v_mov_b32_e32 v159, 0
	v_lshl_add_u64 v[160:161], v[160:161], 0, v[158:159]
	global_store_dwordx4 v[160:161], v[112:115], off
	global_store_dwordx4 v[160:161], v[116:119], off offset:1024
	global_store_dwordx4 v[160:161], v[120:123], off offset:2048
	global_store_dwordx4 v[160:161], v[124:127], off offset:3072
	v_mov_b32_e32 v8, v156
	v_mov_b32_e32 v152, v154
	v_mov_b32_e32 v153, v155
	s_add_i32 s92, s92, s96
	s_cmpk_lt_i32 s92, 0x800
	s_cbranch_scc0 .LBB0_2055
	s_branch .Lln_p18_loopA

	.amdhsa_kernel _Z4mega6Params
		.amdhsa_group_segment_fixed_size 0
		.amdhsa_private_segment_fixed_size 0
		.amdhsa_kernarg_size 584
		.amdhsa_user_sgpr_count 2
		.amdhsa_user_sgpr_dispatch_ptr 0
		.amdhsa_user_sgpr_queue_ptr 0
		.amdhsa_user_sgpr_kernarg_segment_ptr 1
		.amdhsa_user_sgpr_dispatch_id 0
		.amdhsa_user_sgpr_kernarg_preload_length 0
		.amdhsa_user_sgpr_kernarg_preload_offset 0
		.amdhsa_user_sgpr_private_segment_size 0
		.amdhsa_uses_dynamic_stack 0
		.amdhsa_enable_private_segment 0
		.amdhsa_system_sgpr_workgroup_id_x 1
		.amdhsa_system_sgpr_workgroup_id_y 0
		.amdhsa_system_sgpr_workgroup_id_z 0
		.amdhsa_system_sgpr_workgroup_info 0
		.amdhsa_system_vgpr_workitem_id 0
		.amdhsa_next_free_vgpr 256
		.amdhsa_next_free_sgpr 100
		.amdhsa_accum_offset 256
		.amdhsa_reserve_vcc 1
		.amdhsa_float_round_mode_32 0
		.amdhsa_float_round_mode_16_64 0
		.amdhsa_float_denorm_mode_32 3
		.amdhsa_float_denorm_mode_16_64 3
		.amdhsa_dx10_clamp 1
		.amdhsa_ieee_mode 1
		.amdhsa_fp16_overflow 0
		.amdhsa_tg_split 0
		.amdhsa_exception_fp_ieee_invalid_op 0
		.amdhsa_exception_fp_denorm_src 0
		.amdhsa_exception_fp_ieee_div_zero 0
		.amdhsa_exception_fp_ieee_overflow 0
		.amdhsa_exception_fp_ieee_underflow 0
		.amdhsa_exception_fp_ieee_inexact 0
		.amdhsa_exception_int_div_zero 0
	.end_amdhsa_kernel

amdhsa.kernels:
  - .agpr_count:     0
    .args:
      - .offset:         0
        .size:           328
        .value_kind:     by_value
      - .offset:         328
        .size:           4
        .value_kind:     hidden_block_count_x
      - .offset:         332
        .size:           4
        .value_kind:     hidden_block_count_y
      - .offset:         336
        .size:           4
        .value_kind:     hidden_block_count_z
      - .offset:         340
        .size:           2
        .value_kind:     hidden_group_size_x
      - .offset:         342
        .size:           2
        .value_kind:     hidden_group_size_y
      - .offset:         344
        .size:           2
        .value_kind:     hidden_group_size_z
      - .offset:         346
        .size:           2
        .value_kind:     hidden_remainder_x
      - .offset:         348
        .size:           2
        .value_kind:     hidden_remainder_y
      - .offset:         350
        .size:           2
        .value_kind:     hidden_remainder_z
      - .offset:         368
        .size:           8
        .value_kind:     hidden_global_offset_x
      - .offset:         376
        .size:           8
        .value_kind:     hidden_global_offset_y
      - .offset:         384
        .size:           8
        .value_kind:     hidden_global_offset_z
      - .offset:         392
        .size:           2
        .value_kind:     hidden_grid_dims
      - .offset:         416
        .size:           8
        .value_kind:     hidden_multigrid_sync_arg
      - .offset:         448
        .size:           4
        .value_kind:     hidden_dynamic_lds_size
    .group_segment_fixed_size: 0
    .kernarg_segment_align: 8
    .kernarg_segment_size: 584
    .language:       OpenCL C
    .language_version:
      - 2
      - 0
    .max_flat_workgroup_size: 512
    .name:           _Z4mega6Params
    .private_segment_fixed_size: 0
    .sgpr_count:     106
    .sgpr_spill_count: 150
    .symbol:         _Z4mega6Params.kd
    .uniform_work_group_size: 1
    .uses_dynamic_stack: false
    .vgpr_count:     256
    .vgpr_spill_count: 0
    .wavefront_size: 64
